# P2: the four second-round ssd_a chunk-local pair items split into single-head sub-items (16 work items) to remove the 260-on-256 quantization tail
# speedup vs baseline: 1.0209x; 1.0072x over previous
; __global__ void __launch_bounds__(512) hymba_fwd(Params p) {
;     ...
;                 for (;;) {
;                     const int pr = next_item(cnt, lds);
;                     if (2 * pr >= n0 + n1 + n2) break;
;                     const int it = 2 * pr + half;
;                     if (it < n0) { if (PM(2)) ssd_a_item(q, layer, it, ldsh); }
;                     else if (it < n0 + n1) { if (PM(3)) mlakv_tile(q, it - n0, ldsh); }
;                     else { if (PM(4)) mlaq_tile(q, it - n0 - n1, ldsh); }
;                 }
.LBB0_511:
	s_or_b64 exec, exec, s[0:1]
	s_waitcnt lgkmcnt(0)
	s_barrier
	ds_read_b32 v76, v247
	s_movk_i32 s0, 0x49d
	s_waitcnt lgkmcnt(0)
	v_cmp_lt_i32_e32 vcc, s0, v76
	s_mov_b64 s[0:1], -1
	s_cbranch_vccnz .LBB0_506
	v_readfirstlane_b32 s98, v76
	s_mov_b32 s99, 0
	s_cmpk_lt_u32 s98, 0x100
	s_cbranch_scc1 .Lp2_adj_done
	s_cmpk_lt_u32 s98, 0x110
	s_cbranch_scc1 .Lp2_sub
	s_sub_i32 s98, s98, 12
	s_branch .Lp2_adj_set
.Lp2_sub:
	s_sub_i32 s98, s98, 0x100
	s_and_b32 s99, s98, 3
	s_or_b32 s99, s99, 0x100
	s_lshr_b32 s98, s98, 2
	s_add_i32 s98, s98, 0x100
.Lp2_adj_set:
	v_mov_b32_e32 v76, s98
.Lp2_adj_done:
	s_nop 0
	v_writelane_b32 v255, s99, 57
	v_lshl_add_u32 v3, v76, 1, v1
	s_movk_i32 s0, 0x207
	v_cmp_lt_i32_e32 vcc, s0, v3
	s_and_saveexec_b64 s[0:1], vcc
	s_xor_b64 s[0:1], exec, s[0:1]
	s_cbranch_execz .LBB0_534
	s_movk_i32 s2, 0x617
	v_cmp_lt_u32_e32 vcc, s2, v3
	s_and_saveexec_b64 s[2:3], vcc
	s_xor_b64 s[2:3], exec, s[2:3]
	s_cbranch_execz .LBB0_524
	v_add_u32_e32 v6, 0xfffff9e8, v3
	s_mov_b32 s4, 0xaaaaaaab
	v_mov_b32_e32 v83, v210
	v_mov_b32_e32 v4, v210
	v_mul_hi_u32 v2, v6, s4
	s_barrier
	s_load_dwordx2 s[4:5], s[82:83], 0xb0
	v_lshrrev_b32_e32 v7, 2, v2
	v_bfe_u32 v8, v4, 1, 7
	v_mov_b32_e32 v4, v210
	v_lshlrev_b32_e32 v82, 7, v7
	v_and_b32_e32 v9, 1, v4
	v_mul_u32_u24_e32 v4, 0xc0, v9
	v_lshlrev_b32_e32 v4, 1, v4
	v_mov_b32_e32 v5, v197
	v_mul_u32_u24_e32 v196, 0x2140, v8
	v_mad_u64_u32 v[4:5], s[8:9], v82, s20, v[4:5]
	v_mad_u64_u32 v[2:3], s[8:9], v82, s20, 0
	v_lshl_add_u64 v[4:5], v[4:5], 0, v[196:197]
	s_waitcnt lgkmcnt(0)
	v_lshl_add_u64 v[4:5], s[4:5], 0, v[4:5]
	s_mov_b64 s[8:9], 0x1c20
	v_lshl_add_u64 v[4:5], v[4:5], 0, s[8:9]
	v_mov_b32_e32 v10, 0
	s_mov_b32 s8, -8

; DI float bf2f(bf16_t v) { return __uint_as_float(((unsigned)v) << 16); }
; DI int crow(int reg, int hh) { return (reg & 3) + 8 * (reg >> 2) + 4 * hh; }
; DI void ssd_a_item(PP p, int layer, int item, unsigned char* lds) {
;     ...
;     bf16_t* Bt = Bs;
; #pragma unroll
;     for (int i = 0; i < 8; ++i) {
;         const int id = tid + 256 * i, n = id & 127, lc = (id >> 7) * 8;
;         *(u32x4*)(Bt + n * SSTR + lc) = btr[i];
;     }
;     for (int j = hhalf * 4; j < hhalf * 4 + 4; ++j) {
;         const int head = g * 8 + j;
;         const float* Acs = AcsT + j * 128;
;         const float acs_last = Acs[127];
;         {
; #pragma unroll 2
;             for (int i = 0; i < 4; ++i) {
;                 const int id = tid + 256 * i, pch = id & 63, lc = (id >> 6) * 8;
;                 const int cidx = head * 64 + pch;
;                 float wt[4];
; #pragma unroll
;                 for (int k = 0; k < 4; ++k) wt[k] = p->conv_w[(layer * 4 + k) * 1536 + cidx];
;                 const float bias = p->conv_b[layer * 1536 + cidx];
;                 float raw[11];
; #pragma unroll
;                 for (int t = 0; t < 11; ++t) {
;                     const int rr = lc - 3 + t;
;                     float v = 0.f;
;                     if (rr >= 0) v = bf2f(p->proj[(r0 + rr) * PS + PC_X + cidx]);
;                     else if (!first_chunk) v = bf2f(p->halo[(size_t)(((int)(r0 >> 7) - 1) * 3 + rr + 3) * 1024 + cidx]);
;     ...
;                 for (int r = 0; r < 16; ++r) {
;                     const int sl = crow(r, hh);
;                     const float arg = fminf(acs_l - Acs[sb * 32 + sl], 0.f);
;                     const bool ok = (sb < w) || (sl <= l31);
;                     m[r] = ok ? gt[sb][r] * __expf(arg) : 0.f;
.LBB0_565:
	s_or_b64 exec, exec, s[4:5]
	s_movk_i32 s4, 0x110
	v_lshlrev_b32_e32 v66, 16, v115
	v_lshlrev_b32_e32 v67, 16, v117
	v_lshlrev_b32_e32 v68, 16, v118
	v_lshlrev_b32_e32 v69, 16, v121
	v_mad_u32_u24 v107, v107, s4, v119
	v_or_b32_sdwa v66, v66, v110 dst_sel:DWORD dst_unused:UNUSED_PAD src0_sel:DWORD src1_sel:WORD_0
	v_or_b32_sdwa v67, v67, v111 dst_sel:DWORD dst_unused:UNUSED_PAD src0_sel:DWORD src1_sel:WORD_0
	v_or_b32_sdwa v68, v68, v114 dst_sel:DWORD dst_unused:UNUSED_PAD src0_sel:DWORD src1_sel:WORD_0
	v_or_b32_sdwa v69, v69, v120 dst_sel:DWORD dst_unused:UNUSED_PAD src0_sel:DWORD src1_sel:WORD_0
	v_lshlrev_b32_e32 v70, 16, v129
	v_lshlrev_b32_e32 v71, 16, v188
	v_lshlrev_b32_e32 v72, 16, v187
	v_lshlrev_b32_e32 v73, 16, v186
	v_lshl_add_u32 v108, v108, 1, v107
	v_or_b32_sdwa v70, v70, v125 dst_sel:DWORD dst_unused:UNUSED_PAD src0_sel:DWORD src1_sel:WORD_0
	v_or_b32_sdwa v71, v71, v126 dst_sel:DWORD dst_unused:UNUSED_PAD src0_sel:DWORD src1_sel:WORD_0
	v_or_b32_sdwa v72, v72, v127 dst_sel:DWORD dst_unused:UNUSED_PAD src0_sel:DWORD src1_sel:WORD_0
	v_or_b32_sdwa v73, v73, v128 dst_sel:DWORD dst_unused:UNUSED_PAD src0_sel:DWORD src1_sel:WORD_0
	v_lshlrev_b32_e32 v74, 16, v185
	v_lshlrev_b32_e32 v75, 16, v184
	v_lshlrev_b32_e32 v76, 16, v183
	v_lshlrev_b32_e32 v77, 16, v173
	v_lshlrev_b32_e32 v78, 16, v170
	v_lshlrev_b32_e32 v79, 16, v167
	v_lshlrev_b32_e32 v80, 16, v165
	v_lshlrev_b32_e32 v81, 16, v164
	v_lshlrev_b32_e32 v82, 16, v158
	v_lshlrev_b32_e32 v83, 16, v156
	v_lshlrev_b32_e32 v84, 16, v155
	v_lshlrev_b32_e32 v85, 16, v174
	v_lshlrev_b32_e32 v86, 16, v172
	v_lshlrev_b32_e32 v87, 16, v171
	v_lshlrev_b32_e32 v88, 16, v168
	v_lshlrev_b32_e32 v89, 16, v166
	v_lshlrev_b32_e32 v90, 16, v162
	v_lshlrev_b32_e32 v91, 16, v160
	v_lshlrev_b32_e32 v92, 16, v157
	s_waitcnt lgkmcnt(7)
	v_lshlrev_b32_e32 v93, 16, v182
	s_waitcnt lgkmcnt(6)
	v_lshlrev_b32_e32 v94, 16, v178
	s_waitcnt lgkmcnt(4)
	v_lshlrev_b32_e32 v95, 16, v179
	s_waitcnt lgkmcnt(2)
	v_lshlrev_b32_e32 v96, 16, v180
	s_waitcnt lgkmcnt(0)
	v_lshlrev_b32_e32 v97, 16, v181
	s_barrier
	ds_write_b128 v108, v[66:69] offset:34816
	v_lshl_add_u32 v66, v109, 1, v107
	v_or_b32_sdwa v74, v74, v122 dst_sel:DWORD dst_unused:UNUSED_PAD src0_sel:DWORD src1_sel:WORD_0
	v_or_b32_sdwa v75, v75, v123 dst_sel:DWORD dst_unused:UNUSED_PAD src0_sel:DWORD src1_sel:WORD_0
	v_or_b32_sdwa v76, v76, v124 dst_sel:DWORD dst_unused:UNUSED_PAD src0_sel:DWORD src1_sel:WORD_0
	v_or_b32_sdwa v77, v77, v161 dst_sel:DWORD dst_unused:UNUSED_PAD src0_sel:DWORD src1_sel:WORD_0
	v_or_b32_sdwa v78, v78, v154 dst_sel:DWORD dst_unused:UNUSED_PAD src0_sel:DWORD src1_sel:WORD_0
	v_or_b32_sdwa v79, v79, v152 dst_sel:DWORD dst_unused:UNUSED_PAD src0_sel:DWORD src1_sel:WORD_0
	v_or_b32_sdwa v80, v80, v150 dst_sel:DWORD dst_unused:UNUSED_PAD src0_sel:DWORD src1_sel:WORD_0
	v_or_b32_sdwa v81, v81, v148 dst_sel:DWORD dst_unused:UNUSED_PAD src0_sel:DWORD src1_sel:WORD_0
	v_or_b32_sdwa v82, v82, v146 dst_sel:DWORD dst_unused:UNUSED_PAD src0_sel:DWORD src1_sel:WORD_0
	v_or_b32_sdwa v83, v83, v144 dst_sel:DWORD dst_unused:UNUSED_PAD src0_sel:DWORD src1_sel:WORD_0
	v_or_b32_sdwa v84, v84, v131 dst_sel:DWORD dst_unused:UNUSED_PAD src0_sel:DWORD src1_sel:WORD_0
	v_or_b32_sdwa v85, v85, v159 dst_sel:DWORD dst_unused:UNUSED_PAD src0_sel:DWORD src1_sel:WORD_0
	v_or_b32_sdwa v86, v86, v153 dst_sel:DWORD dst_unused:UNUSED_PAD src0_sel:DWORD src1_sel:WORD_0
	v_or_b32_sdwa v87, v87, v151 dst_sel:DWORD dst_unused:UNUSED_PAD src0_sel:DWORD src1_sel:WORD_0
	v_or_b32_sdwa v88, v88, v149 dst_sel:DWORD dst_unused:UNUSED_PAD src0_sel:DWORD src1_sel:WORD_0
	v_or_b32_sdwa v89, v89, v147 dst_sel:DWORD dst_unused:UNUSED_PAD src0_sel:DWORD src1_sel:WORD_0
	v_or_b32_sdwa v90, v90, v145 dst_sel:DWORD dst_unused:UNUSED_PAD src0_sel:DWORD src1_sel:WORD_0
	v_or_b32_sdwa v91, v91, v143 dst_sel:DWORD dst_unused:UNUSED_PAD src0_sel:DWORD src1_sel:WORD_0
	v_or_b32_sdwa v92, v92, v130 dst_sel:DWORD dst_unused:UNUSED_PAD src0_sel:DWORD src1_sel:WORD_0
	v_or_b32_sdwa v93, v93, v169 dst_sel:DWORD dst_unused:UNUSED_PAD src0_sel:DWORD src1_sel:WORD_0
	v_or_b32_sdwa v94, v94, v163 dst_sel:DWORD dst_unused:UNUSED_PAD src0_sel:DWORD src1_sel:WORD_0
	v_or_b32_sdwa v95, v95, v175 dst_sel:DWORD dst_unused:UNUSED_PAD src0_sel:DWORD src1_sel:WORD_0
	v_or_b32_sdwa v96, v96, v176 dst_sel:DWORD dst_unused:UNUSED_PAD src0_sel:DWORD src1_sel:WORD_0
	v_or_b32_sdwa v97, v97, v177 dst_sel:DWORD dst_unused:UNUSED_PAD src0_sel:DWORD src1_sel:WORD_0
	ds_write_b128 v66, v[70:73] offset:34848
	ds_write_b128 v66, v[74:77] offset:34880
	ds_write_b128 v66, v[78:81] offset:34912
	ds_write_b128 v66, v[82:85] offset:34944
	ds_write_b128 v66, v[86:89] offset:34976
	ds_write_b128 v66, v[90:93] offset:35008
	ds_write_b128 v66, v[94:97] offset:35040
	v_alignbit_b32 v66, v103, v102, 7
	v_lshl_add_u32 v72, v66, 1, v66
	v_add_u32_e32 v70, -3, v72
	v_ashrrev_i32_e32 v71, 31, v70
	v_lshlrev_b32_e32 v144, 4, v106
	v_lshlrev_b64 v[106:107], 11, v[70:71]
	v_add_u32_e32 v70, -2, v72
	v_ashrrev_i32_e32 v71, 31, v70
	v_lshlrev_b64 v[108:109], 11, v[70:71]
	v_add_u32_e32 v70, -1, v72
	v_lshlrev_b32_e32 v143, 2, v116
	v_ashrrev_i32_e32 v71, 31, v70
	v_lshlrev_b64 v[110:111], 11, v[70:71]
	v_or_b32_e32 v70, 2, v143
	v_cmp_le_u32_e64 s[62:63], v70, v112
	v_or_b32_e32 v70, 3, v143
	v_cmp_le_u32_e64 s[66:67], v70, v112
	v_or_b32_e32 v70, 9, v143
	v_cmp_le_u32_e64 s[26:27], v70, v112
	v_or_b32_e32 v70, 10, v143
	v_cmp_le_u32_e64 s[28:29], v70, v112
	v_or_b32_e32 v70, 11, v143
	v_cmp_le_u32_e64 s[30:31], v70, v112
	v_or_b32_e32 v70, 16, v143
	v_cmp_le_u32_e64 s[34:35], v70, v112
	v_or_b32_e32 v70, 17, v143
	v_or_b32_e32 v68, v102, v141
	v_mov_b64_e32 v[66:67], s[50:51]
	v_cmp_le_u32_e64 s[36:37], v70, v112
	v_or_b32_e32 v70, 18, v143
	v_mad_u64_u32 v[66:67], s[4:5], v68, s20, v[66:67]
	v_cmp_le_u32_e64 s[38:39], v70, v112
	v_or_b32_e32 v70, 19, v143
	s_load_dwordx2 s[4:5], s[82:83], 0x130
	v_cmp_le_u32_e64 s[40:41], v70, v112
	v_or_b32_e32 v70, 24, v143
	v_cmp_le_u32_e64 s[42:43], v70, v112
	v_or_b32_e32 v70, 25, v143
	v_mov_b32_e32 v68, v67
	v_cmp_le_u32_e64 s[44:45], v70, v112
	v_or_b32_e32 v70, 26, v143
	v_mad_u64_u32 v[68:69], s[16:17], v103, s20, v[68:69]
	v_or_b32_e32 v72, 8, v143
	v_cmp_le_u32_e64 s[46:47], v70, v112
	v_or_b32_e32 v70, 27, v143
	v_lshlrev_b32_e32 v196, 5, v139
	v_cmp_lt_u32_e32 vcc, 63, v98
	v_cmp_le_u32_e64 s[18:19], v143, v112
	v_cmp_lt_u32_e64 s[58:59], v143, v112
	v_cmp_le_u32_e64 s[70:71], v72, v112
	v_cmp_le_u32_e64 s[48:49], v70, v112
	s_movk_i32 s16, 0x7f
	v_mov_b32_e32 v67, v68
	s_waitcnt lgkmcnt(0)
; DI void ssd_a_item(PP p, int layer, int item, unsigned char* lds) {
;     ...
;     for (int j = hhalf * 4; j < hhalf * 4 + 4; ++j) {
;         const int head = g * 8 + j;
;         const float* Acs = AcsT + j * 128;
;         const float acs_last = Acs[127];
;         {
; #pragma unroll 2
;             for (int i = 0; i < 4; ++i) {
;                 const int id = tid + 256 * i, pch = id & 63, lc = (id >> 6) * 8;
;                 const int cidx = head * 64 + pch;
;                 float wt[4];
; #pragma unroll
;                 for (int k = 0; k < 4; ++k) wt[k] = p->conv_w[(layer * 4 + k) * 1536 + cidx];
;                 const float bias = p->conv_b[layer * 1536 + cidx];
;                 float raw[11];
; #pragma unroll
;                 for (int t = 0; t < 11; ++t) {
;                     const int rr = lc - 3 + t;
;                     float v = 0.f;
;                     if (rr >= 0) v = bf2f(p->proj[(r0 + rr) * PS + PC_X + cidx]);
;                     else if (!first_chunk) v = bf2f(p->halo[(size_t)(((int)(r0 >> 7) - 1) * 3 + rr + 3) * 1024 + cidx]);
;                     raw[t] = v;
;                 }
;                 float xc[8], xd[8];
; #pragma unroll
;                 for (int e = 0; e < 8; ++e) {
;                     float v = bias + wt[0] * raw[e] + wt[1] * raw[e + 1] + wt[2] * raw[e + 2] + wt[3] * raw[e + 3];
;                     v = siluf(v);
;                     const float dtv = p->dtbuf[(r0 + lc + e) * 16 + head];
;                     xc[e] = v; xd[e] = v * dtv;
;                 }
;                 *(bf16x8*)(Xt + pch * SSTR + lc) = pack8(xd[0], xd[1], xd[2], xd[3], xd[4], xd[5], xd[6], xd[7]);
;                 *(bf16x8*)(Xc + pch * SSTR + lc) = pack8(xc[0], xc[1], xc[2], xc[3], xc[4], xc[5], xc[6], xc[7]);
;             }
;         }
;         __syncthreads();
;         f32x16 ya[2]; ya[0] = ya[1] = zero16();
;         const float acs_l = Acs[w * 32 + l31];
; #pragma unroll
;         for (int sb = 0; sb < 4; ++sb) {
;             if (sb <= w) {
;                 f32x16 m;
; #pragma unroll
;                 for (int r = 0; r < 16; ++r) {
;                     const int sl = crow(r, hh);
;                     const float arg = fminf(acs_l - Acs[sb * 32 + sl], 0.f);
;                     const bool ok = (sb < w) || (sl <= l31);
;                     m[r] = ok ? gt[sb][r] * __expf(arg) : 0.f;
	v_lshl_add_u64 v[68:69], s[4:5], 0, v[196:197]
	s_or_b64 s[54:55], vcc, s[18:19]
	s_or_b64 s[56:57], vcc, s[58:59]
	s_or_b64 s[84:85], vcc, s[62:63]
	s_or_b64 s[86:87], vcc, s[66:67]
	s_or_b64 s[88:89], vcc, s[70:71]
	s_or_b64 s[90:91], vcc, s[26:27]
	s_or_b64 s[92:93], vcc, s[28:29]
	s_or_b64 s[94:95], vcc, s[30:31]
	s_or_b64 s[96:97], vcc, s[34:35]
	s_or_b64 s[52:53], vcc, s[36:37]
	s_or_b64 s[4:5], vcc, s[38:39]
	s_or_b64 s[74:75], vcc, s[40:41]
	s_or_b64 s[76:77], vcc, s[42:43]
	s_or_b64 s[78:79], vcc, s[44:45]
	s_or_b64 s[80:81], vcc, s[46:47]
	s_or_b64 s[64:65], vcc, s[48:49]
	v_cmp_lt_u32_e32 vcc, s16, v98
	s_or_b64 s[16:17], vcc, s[18:19]
	v_writelane_b32 v254, s16, 3
	v_lshlrev_b32_e32 v196, 11, v99
	v_lshrrev_b32_e32 v74, 6, v98
	v_writelane_b32 v254, s17, 4
	s_or_b64 s[16:17], vcc, s[58:59]
	v_writelane_b32 v254, s16, 5
	v_lshlrev_b32_e32 v70, 1, v113
	v_lshl_add_u64 v[112:113], v[68:69], 0, v[196:197]
	v_writelane_b32 v254, s17, 6
	s_or_b64 s[16:17], vcc, s[62:63]
	v_writelane_b32 v254, s16, 7
	v_lshlrev_b32_e32 v104, 3, v116
	v_add3_u32 v145, v119, v104, v70
	v_writelane_b32 v254, s17, 8
	s_or_b64 s[16:17], vcc, s[66:67]
	v_writelane_b32 v254, s16, 9
	v_lshl_or_b32 v70, v105, 9, v137
	v_add_lshl_u32 v196, v70, v139, 1
	v_writelane_b32 v254, s17, 10
	s_or_b64 s[16:17], vcc, s[70:71]
	v_writelane_b32 v254, s16, 11
	v_mov_b32_e32 v105, v197
	v_mul_u32_u24_e32 v73, 0x88, v139
	v_writelane_b32 v254, s17, 12
	s_mov_b32 s16, 0x10a00
	v_mad_u64_u32 v[68:69], s[16:17], v74, s16, v[100:101]
	s_or_b64 s[16:17], vcc, s[26:27]
	s_nop 0
	v_writelane_b32 v254, s16, 13
	v_lshl_add_u64 v[68:69], v[68:69], 0, v[196:197]
	v_lshlrev_b32_e32 v196, 3, v74
	v_writelane_b32 v254, s17, 14
	s_or_b64 s[16:17], vcc, s[28:29]
	v_writelane_b32 v254, s16, 15
	v_lshl_add_u64 v[70:71], v[102:103], 0, v[196:197]
	v_lshlrev_b64 v[70:71], 6, v[70:71]
	v_writelane_b32 v254, s17, 16
	s_or_b64 s[16:17], vcc, s[30:31]
	v_writelane_b32 v254, s16, 17
	v_add_lshl_u32 v196, v134, v140, 2
	v_lshl_add_u64 v[70:71], v[70:71], 0, v[196:197]
	v_writelane_b32 v254, s17, 18
	s_or_b64 s[16:17], vcc, s[34:35]
	v_writelane_b32 v254, s16, 19
	v_lshl_add_u64 v[114:115], s[68:69], 0, v[70:71]
	v_mul_u32_u24_e32 v70, 0x440, v116
	v_writelane_b32 v254, s17, 20
	s_or_b64 s[16:17], vcc, s[36:37]
	v_writelane_b32 v254, s16, 21
	v_lshlrev_b32_e32 v71, 1, v141
	v_add3_u32 v146, v119, v70, v71
	v_writelane_b32 v254, s17, 22
	s_or_b64 s[16:17], vcc, s[38:39]
	v_writelane_b32 v254, s16, 23
	v_mul_u32_u24_e32 v70, 0x110, v72
	v_lshl_add_u64 v[66:67], v[66:67], 0, v[104:105]
	v_writelane_b32 v254, s17, 24
	s_or_b64 s[16:17], vcc, s[40:41]
	v_writelane_b32 v254, s16, 25
	v_add3_u32 v147, v119, v70, v71
	v_lshl_add_u64 v[116:117], v[66:67], 0, s[60:61]
	v_writelane_b32 v254, s17, 26
	s_or_b64 s[16:17], vcc, s[42:43]
	v_writelane_b32 v254, s16, 27
	v_lshlrev_b32_e32 v66, 4, v99
	v_lshlrev_b32_e32 v67, 1, v73
	v_writelane_b32 v254, s17, 28
	s_or_b64 s[16:17], vcc, s[44:45]
	v_writelane_b32 v254, s16, 29
	v_add_u32_e32 v148, 0x880, v147
	v_add_u32_e32 v149, 0x1100, v147
	v_writelane_b32 v254, s17, 30
	s_or_b64 s[16:17], vcc, s[46:47]
	v_writelane_b32 v254, s16, 31
	v_add_u32_e32 v150, 0x1980, v147
	v_add_u32_e32 v151, 0x2200, v147
	v_writelane_b32 v254, s17, 32
	s_or_b64 s[16:17], vcc, s[48:49]
	v_writelane_b32 v254, s16, 33
	v_add_u32_e32 v152, 0x2a80, v147
	v_add_u32_e32 v153, 0x3300, v147
	v_writelane_b32 v254, s17, 34
	v_writelane_b32 v254, s18, 35
	s_or_b64 s[16:17], s[14:15], s[18:19]
	v_add_u32_e32 v154, v145, v104
	v_writelane_b32 v254, s19, 36
	v_writelane_b32 v254, s16, 37
	v_mul_u32_u24_e32 v118, 0x10a00, v74
	v_lshl_add_u64 v[120:121], s[50:51], 0, v[68:69]
	v_writelane_b32 v254, s17, 38
	v_writelane_b32 v254, s58, 39
	s_or_b64 s[16:17], s[14:15], s[58:59]
	v_lshl_add_u32 v105, v99, 3, -1
	v_writelane_b32 v254, s59, 40
	v_writelane_b32 v254, s16, 41
	v_add3_u32 v155, v66, v67, v119
	v_mov_b32_e32 v156, v134
	v_readlane_b32 s98, v255, 57
	v_mov_b32_e32 v220, v136
	s_bitcmp1_b32 s98, 8
	s_cbranch_scc0 .Lssda_nosub
	s_and_b32 s98, s98, 3
	s_nop 0
	v_add_u32_e32 v156, s98, v134
	v_mov_b32_e32 v220, v156
	s_mov_b32 s99, 0
	s_lshl_b32 s98, s98, 2
	v_lshl_add_u64 v[114:115], v[114:115], 0, s[98:99]
	s_lshl_b32 s98, s98, 5
	v_lshl_add_u64 v[120:121], v[120:121], 0, s[98:99]
.Lssda_nosub:
	v_writelane_b32 v254, s17, 42
	v_writelane_b32 v254, s62, 43
	s_or_b64 s[16:17], s[14:15], s[62:63]
	s_mov_b64 s[58:59], 0
	v_writelane_b32 v254, s63, 44
	v_writelane_b32 v254, s16, 45
	s_nop 1
	v_writelane_b32 v254, s17, 46
	v_writelane_b32 v254, s66, 47
	s_or_b64 s[16:17], s[14:15], s[66:67]
	s_nop 0
	v_writelane_b32 v254, s67, 48
	v_writelane_b32 v254, s16, 49
	s_nop 1
	v_writelane_b32 v254, s17, 50
	v_writelane_b32 v254, s70, 51
	s_or_b64 s[16:17], s[14:15], s[70:71]
	s_nop 0
	v_writelane_b32 v254, s71, 52
	v_writelane_b32 v254, s16, 53
	s_nop 1
	v_writelane_b32 v254, s17, 54
	s_or_b64 s[16:17], s[14:15], s[26:27]
	v_writelane_b32 v254, s16, 55
	s_nop 1
	v_writelane_b32 v254, s17, 56
	s_or_b64 s[16:17], s[14:15], s[28:29]
	v_writelane_b32 v254, s16, 57
	s_nop 1
	v_writelane_b32 v254, s17, 58
	s_or_b64 s[16:17], s[14:15], s[30:31]
	v_writelane_b32 v254, s16, 59
	s_nop 1
	v_writelane_b32 v254, s17, 60
	s_or_b64 s[16:17], s[14:15], s[34:35]
	v_writelane_b32 v254, s16, 61
	s_nop 1
	v_writelane_b32 v254, s17, 62
	s_or_b64 s[16:17], s[14:15], s[36:37]
	v_writelane_b32 v254, s16, 63
	s_nop 1
	v_writelane_b32 v255, s17, 0
	s_or_b64 s[16:17], s[14:15], s[38:39]
	v_writelane_b32 v255, s16, 1
	s_nop 1
	v_writelane_b32 v255, s17, 2
	s_or_b64 s[16:17], s[14:15], s[40:41]
	v_writelane_b32 v255, s16, 3
	s_nop 1
	v_writelane_b32 v255, s17, 4
	s_or_b64 s[16:17], s[14:15], s[42:43]
	v_writelane_b32 v255, s16, 5
	s_nop 1
	v_writelane_b32 v255, s17, 6
	s_or_b64 s[16:17], s[14:15], s[44:45]
	v_writelane_b32 v255, s16, 7
	s_nop 1
	v_writelane_b32 v255, s17, 8
	s_or_b64 s[16:17], s[14:15], s[46:47]
	v_writelane_b32 v255, s16, 9
	s_nop 1
	v_writelane_b32 v255, s17, 10
	s_or_b64 s[16:17], s[14:15], s[48:49]
	v_writelane_b32 v255, s16, 11
	s_nop 1
	v_writelane_b32 v255, s17, 12
	s_branch .LBB0_568

; DI unsigned pk2(float a, float b) { f32x2_t v = {a, b}; bf16x2_t r = __builtin_convertvector(v, bf16x2_t); return __builtin_bit_cast(unsigned, r); }
; DI float bf2f(bf16_t v) { return __uint_as_float(((unsigned)v) << 16); }
; DI void ssd_a_item(PP p, int layer, int item, unsigned char* lds) {
;     ...
;         const float dsk = p->d_skip[layer * 16 + head];
;         const int lrow = w * 32 + l31;
; #pragma unroll
;         for (int pb = 0; pb < 2; ++pb)
; #pragma unroll
;             for (int q = 0; q < 4; ++q) {
;                 const int p0 = pb * 32 + 8 * q + 4 * hh;
;                 float v[4];
; #pragma unroll
;                 for (int e = 0; e < 4; ++e) v[e] = ya[pb][4 * q + e] + dsk * bf2f(Xc[(p0 + e) * SSTR + lrow]);
;                 u32x2 o; o[0] = pk2(v[0], v[1]); o[1] = pk2(v[2], v[3]);
;                 *(u32x2*)(p->proj + (r0 + lrow) * PS + PC_X + head * 64 + p0) = o;
;             }
;     ...
;             for (int kk = 0; kk < 8; ++kk) {
;                 float wl[8];
; #pragma unroll
;                 for (int e = 0; e < 8; ++e) wl[e] = __expf(acs_last - Acs[kk * 16 + 8 * hh + e]);
;                 const bf16x8 a = ld16(Bt + (w * 32 + l31) * SSTR + kk * 16 + 8 * hh);
.LBB0_567:
	s_or_b64 exec, exec, s[70:71]
	v_readlane_b32 s16, v253, 51
	v_mov_b32_e32 v99, v197
	v_lshl_add_u32 v130, v104, 2, v159
	v_add_u32_e32 v100, s16, v157
	s_load_dwordx2 s[16:17], s[82:83], 0x40
	v_ashrrev_i32_e32 v101, 31, v100
	v_lshl_add_u64 v[114:115], v[114:115], 0, 4
	s_waitcnt lgkmcnt(0)
	v_lshl_add_u64 v[100:101], v[100:101], 2, s[16:17]
	global_load_dword v100, v[100:101], off
	ds_read_u16 v101, v146 offset:17408
	ds_read_u16 v122, v146 offset:17680
	s_movk_i32 s16, 0x2000
	s_waitcnt lgkmcnt(0)
	v_lshlrev_b32_e32 v123, 16, v122
	v_lshlrev_b32_e32 v122, 16, v101
	s_waitcnt vmcnt(0)
	v_pk_fma_f32 v[82:83], v[100:101], v[122:123], v[82:83] op_sel_hi:[0,1,1]
	ds_read_u16 v101, v146 offset:17952
	ds_read_u16 v122, v146 offset:18224
	s_waitcnt lgkmcnt(0)
	v_lshlrev_b32_e32 v123, 16, v122
	v_lshlrev_b32_e32 v122, 16, v101
	v_pk_fma_f32 v[84:85], v[100:101], v[122:123], v[84:85] op_sel_hi:[0,1,1]
	v_cvt_pk_bf16_f32 v122, v82, v83
	v_cvt_pk_bf16_f32 v123, v84, v85
	v_lshl_add_u64 v[82:83], v[98:99], 1, v[116:117]
	global_store_dwordx2 v[82:83], v[122:123], off
	ds_read_u16 v84, v147 offset:17408
	ds_read_u16 v85, v146 offset:19856
	s_waitcnt lgkmcnt(1)
	v_lshlrev_b32_e32 v84, 16, v84
	s_waitcnt lgkmcnt(0)
	v_lshlrev_b32_e32 v85, 16, v85
	v_pk_fma_f32 v[84:85], v[100:101], v[84:85], v[86:87] op_sel_hi:[0,1,1]
	ds_read_u16 v86, v146 offset:20128
	ds_read_u16 v87, v146 offset:20400
	v_cvt_pk_bf16_f32 v84, v84, v85
	s_waitcnt lgkmcnt(1)
	v_lshlrev_b32_e32 v86, 16, v86
	s_waitcnt lgkmcnt(0)
	v_lshlrev_b32_e32 v87, 16, v87
	v_pk_fma_f32 v[86:87], v[100:101], v[86:87], v[88:89] op_sel_hi:[0,1,1]
	v_cvt_pk_bf16_f32 v85, v86, v87
	global_store_dwordx2 v[82:83], v[84:85], off offset:16
	ds_read_u16 v84, v148 offset:17408
	ds_read_u16 v85, v146 offset:22032
	ds_read_u16 v86, v146 offset:22304
	ds_read_u16 v87, v146 offset:22576
	s_waitcnt lgkmcnt(3)
	v_lshlrev_b32_e32 v84, 16, v84
	s_waitcnt lgkmcnt(2)
	v_lshlrev_b32_e32 v85, 16, v85
	s_waitcnt lgkmcnt(0)
	v_lshlrev_b32_e32 v87, 16, v87
	v_lshlrev_b32_e32 v86, 16, v86
	v_pk_fma_f32 v[84:85], v[100:101], v[84:85], v[90:91] op_sel_hi:[0,1,1]
	v_pk_fma_f32 v[86:87], v[100:101], v[86:87], v[92:93] op_sel_hi:[0,1,1]
	v_cvt_pk_bf16_f32 v84, v84, v85
	v_cvt_pk_bf16_f32 v85, v86, v87
	global_store_dwordx2 v[82:83], v[84:85], off offset:32
	ds_read_u16 v84, v149 offset:17408
	ds_read_u16 v85, v146 offset:24208
	ds_read_u16 v86, v146 offset:24480
	ds_read_u16 v87, v146 offset:24752
	s_waitcnt lgkmcnt(3)
	v_lshlrev_b32_e32 v84, 16, v84
	s_waitcnt lgkmcnt(2)
	v_lshlrev_b32_e32 v85, 16, v85
	s_waitcnt lgkmcnt(0)
	v_lshlrev_b32_e32 v87, 16, v87
	v_lshlrev_b32_e32 v86, 16, v86
	v_pk_fma_f32 v[84:85], v[100:101], v[84:85], v[94:95] op_sel_hi:[0,1,1]
	v_pk_fma_f32 v[86:87], v[100:101], v[86:87], v[96:97] op_sel_hi:[0,1,1]
	v_cvt_pk_bf16_f32 v84, v84, v85
	v_cvt_pk_bf16_f32 v85, v86, v87
	global_store_dwordx2 v[82:83], v[84:85], off offset:48
	ds_read_u16 v84, v150 offset:17408
	ds_read_u16 v85, v146 offset:26384
	s_waitcnt lgkmcnt(1)
	v_lshlrev_b32_e32 v84, 16, v84
	s_waitcnt lgkmcnt(0)
	v_lshlrev_b32_e32 v85, 16, v85
	v_pk_fma_f32 v[66:67], v[100:101], v[84:85], v[66:67] op_sel_hi:[0,1,1]
	ds_read_u16 v84, v146 offset:26656
	ds_read_u16 v85, v146 offset:26928
	v_cvt_pk_bf16_f32 v66, v66, v67
	s_waitcnt lgkmcnt(1)
	v_lshlrev_b32_e32 v84, 16, v84
	s_waitcnt lgkmcnt(0)
	v_lshlrev_b32_e32 v85, 16, v85
	v_pk_fma_f32 v[68:69], v[100:101], v[84:85], v[68:69] op_sel_hi:[0,1,1]
	v_cvt_pk_bf16_f32 v67, v68, v69
	global_store_dwordx2 v[82:83], v[66:67], off offset:64
	ds_read_u16 v66, v151 offset:17408
	ds_read_u16 v67, v146 offset:28560
	ds_read_u16 v68, v146 offset:28832
	ds_read_u16 v69, v146 offset:29104
	s_waitcnt lgkmcnt(3)
	v_lshlrev_b32_e32 v66, 16, v66
	s_waitcnt lgkmcnt(2)
	v_lshlrev_b32_e32 v67, 16, v67
	s_waitcnt lgkmcnt(0)
	v_lshlrev_b32_e32 v69, 16, v69
	v_lshlrev_b32_e32 v68, 16, v68
	v_pk_fma_f32 v[66:67], v[100:101], v[66:67], v[70:71] op_sel_hi:[0,1,1]
	v_pk_fma_f32 v[68:69], v[100:101], v[68:69], v[72:73] op_sel_hi:[0,1,1]
	v_cvt_pk_bf16_f32 v66, v66, v67
	v_cvt_pk_bf16_f32 v67, v68, v69
	global_store_dwordx2 v[82:83], v[66:67], off offset:80
	ds_read_u16 v66, v152 offset:17408
	ds_read_u16 v67, v146 offset:30736
	ds_read_u16 v68, v146 offset:31008
	ds_read_u16 v69, v146 offset:31280
	s_waitcnt lgkmcnt(3)
	v_lshlrev_b32_e32 v66, 16, v66
	s_waitcnt lgkmcnt(2)
	v_lshlrev_b32_e32 v67, 16, v67
	s_waitcnt lgkmcnt(0)
	v_lshlrev_b32_e32 v69, 16, v69
	v_lshlrev_b32_e32 v68, 16, v68
	v_pk_fma_f32 v[66:67], v[100:101], v[66:67], v[74:75] op_sel_hi:[0,1,1]
	v_pk_fma_f32 v[68:69], v[100:101], v[68:69], v[76:77] op_sel_hi:[0,1,1]
	v_cvt_pk_bf16_f32 v66, v66, v67
	v_cvt_pk_bf16_f32 v67, v68, v69
	global_store_dwordx2 v[82:83], v[66:67], off offset:96
	ds_read_u16 v66, v153 offset:17408
	ds_read_u16 v67, v146 offset:32912
	ds_read_u16 v68, v146 offset:33184
	ds_read_u16 v69, v146 offset:33456
	s_waitcnt lgkmcnt(3)
	v_lshlrev_b32_e32 v66, 16, v66
	s_waitcnt lgkmcnt(2)
	v_lshlrev_b32_e32 v67, 16, v67
	s_waitcnt lgkmcnt(0)
	v_lshlrev_b32_e32 v69, 16, v69
	v_lshlrev_b32_e32 v68, 16, v68
	v_pk_fma_f32 v[66:67], v[100:101], v[66:67], v[78:79] op_sel_hi:[0,1,1]
	v_pk_fma_f32 v[68:69], v[100:101], v[68:69], v[80:81] op_sel_hi:[0,1,1]
	v_cvt_pk_bf16_f32 v66, v66, v67
	v_cvt_pk_bf16_f32 v67, v68, v69
	global_store_dwordx2 v[82:83], v[66:67], off offset:112
	ds_read_b128 v[66:69], v130
	ds_read_b128 v[70:73], v130 offset:16
	s_waitcnt lgkmcnt(1)
; DI float bflo(unsigned u) { return __uint_as_float(u << 16); }
; DI float bfhi(unsigned u) { return __uint_as_float(u & 0xffff0000u); }
; DI f32x16 mfma32(bf16x8 a, bf16x8 b, f32x16 c) { return __builtin_amdgcn_mfma_f32_32x32x16_bf16(a, b, c, 0, 0, 0); }
; DI f32x16 zero16() { f32x16 z; for (int i = 0; i < 16; ++i) z[i] = 0.f; return z; }
; DI void ssd_a_item(PP p, int layer, int item, unsigned char* lds) {
;     ...
;             f32x16 la[2]; la[0] = la[1] = zero16();
; #pragma unroll
;             for (int kk = 0; kk < 8; ++kk) {
;                 float wl[8];
; #pragma unroll
;                 for (int e = 0; e < 8; ++e) wl[e] = __expf(acs_last - Acs[kk * 16 + 8 * hh + e]);
;                 const bf16x8 a = ld16(Bt + (w * 32 + l31) * SSTR + kk * 16 + 8 * hh);
; #pragma unroll
;                 for (int pb = 0; pb < 2; ++pb) {
;                     const u32x4 xr = *(const u32x4*)(Xt + (pb * 32 + l31) * SSTR + kk * 16 + 8 * hh);
;                     const bf16x8 xb = pack8(bflo(xr[0]) * wl[0], bfhi(xr[0]) * wl[1], bflo(xr[1]) * wl[2], bfhi(xr[1]) * wl[3],
;                                             bflo(xr[2]) * wl[4], bfhi(xr[2]) * wl[5], bflo(xr[3]) * wl[6], bfhi(xr[3]) * wl[7]);
;                     la[pb] = mfma32(a, xb, la[pb]);
;                 }
	v_sub_f32_e32 v66, v158, v66
	v_mul_f32_e32 v66, 0x3fb8aa3b, v66
	v_exp_f32_e32 v90, v66
	v_sub_f32_e32 v66, v158, v67
	v_mul_f32_e32 v66, 0x3fb8aa3b, v66
	v_exp_f32_e32 v91, v66
	v_sub_f32_e32 v66, v158, v68
	v_mul_f32_e32 v66, 0x3fb8aa3b, v66
	v_exp_f32_e32 v92, v66
	v_sub_f32_e32 v66, v158, v69
	v_mul_f32_e32 v66, 0x3fb8aa3b, v66
	v_exp_f32_e32 v93, v66
	s_waitcnt lgkmcnt(0)
	v_sub_f32_e32 v66, v158, v70
	v_mul_f32_e32 v66, 0x3fb8aa3b, v66
	v_exp_f32_e32 v94, v66
	v_sub_f32_e32 v66, v158, v71
	v_mul_f32_e32 v66, 0x3fb8aa3b, v66
	v_exp_f32_e32 v95, v66
	v_sub_f32_e32 v66, v158, v72
	v_mul_f32_e32 v66, 0x3fb8aa3b, v66
	v_exp_f32_e32 v96, v66
	v_sub_f32_e32 v66, v158, v73
	v_mul_f32_e32 v66, 0x3fb8aa3b, v66
	v_exp_f32_e32 v97, v66
	ds_read_b128 v[66:69], v154
	ds_read_b128 v[160:163], v154 offset:32
	ds_read_b128 v[82:85], v142 offset:34816
	ds_read_b128 v[98:101], v142 offset:34848
	ds_read_b128 v[86:89], v154 offset:8704
	ds_read_b128 v[126:129], v130 offset:80
	s_waitcnt lgkmcnt(5)
	v_lshlrev_b32_e32 v70, 16, v66
	v_and_b32_e32 v71, 0xffff0000, v66
	v_pk_mul_f32 v[70:71], v[90:91], v[70:71]
	s_waitcnt lgkmcnt(1)
	v_lshlrev_b32_e32 v122, 16, v86
	v_and_b32_e32 v123, 0xffff0000, v86
	v_pk_mul_f32 v[90:91], v[90:91], v[122:123]
	ds_read_b128 v[122:125], v130 offset:64
	v_lshlrev_b32_e32 v66, 16, v67
	v_and_b32_e32 v67, 0xffff0000, v67
	v_pk_mul_f32 v[72:73], v[92:93], v[66:67]
	v_lshlrev_b32_e32 v66, 16, v68
	v_and_b32_e32 v67, 0xffff0000, v68
	v_pk_mul_f32 v[74:75], v[94:95], v[66:67]
	v_lshlrev_b32_e32 v66, 16, v69
	v_and_b32_e32 v67, 0xffff0000, v69
	v_pk_mul_f32 v[76:77], v[96:97], v[66:67]
	s_waitcnt lgkmcnt(0)
	v_sub_f32_e32 v124, v158, v124
	v_sub_f32_e32 v125, v158, v125
	v_cvt_pk_bf16_f32 v66, v70, v71
	v_cvt_pk_bf16_f32 v67, v72, v73
	v_cvt_pk_bf16_f32 v68, v74, v75
	v_cvt_pk_bf16_f32 v69, v76, v77
	v_mul_f32_e32 v124, 0x3fb8aa3b, v124
	v_mul_f32_e32 v125, 0x3fb8aa3b, v125
	v_sub_f32_e32 v126, v158, v126
	v_sub_f32_e32 v127, v158, v127
	v_mfma_f32_32x32x16_bf16 v[66:81], v[82:85], v[66:69], 0
	v_sub_f32_e32 v122, v158, v122
	v_sub_f32_e32 v123, v158, v123
	v_exp_f32_e32 v124, v124
	v_exp_f32_e32 v125, v125
	v_mul_f32_e32 v126, 0x3fb8aa3b, v126
	v_mul_f32_e32 v127, 0x3fb8aa3b, v127
	v_sub_f32_e32 v128, v158, v128
	v_sub_f32_e32 v129, v158, v129
	v_mul_f32_e32 v122, 0x3fb8aa3b, v122
	v_mul_f32_e32 v123, 0x3fb8aa3b, v123
	v_exp_f32_e32 v126, v126
	v_exp_f32_e32 v127, v127
	v_mul_f32_e32 v128, 0x3fb8aa3b, v128
	v_mul_f32_e32 v129, 0x3fb8aa3b, v129
	v_exp_f32_e32 v122, v122
	v_exp_f32_e32 v123, v123
	v_exp_f32_e32 v128, v128
	v_exp_f32_e32 v129, v129
	v_lshlrev_b32_e32 v164, 16, v160
	v_and_b32_e32 v165, 0xffff0000, v160
	v_lshlrev_b32_e32 v160, 16, v161
	v_and_b32_e32 v161, 0xffff0000, v161
	v_pk_mul_f32 v[166:167], v[124:125], v[160:161]
	v_lshlrev_b32_e32 v160, 16, v162
	v_and_b32_e32 v161, 0xffff0000, v162
	v_lshlrev_b32_e32 v86, 16, v87
	v_and_b32_e32 v87, 0xffff0000, v87
	v_pk_mul_f32 v[168:169], v[126:127], v[160:161]
	v_lshlrev_b32_e32 v160, 16, v163
	v_and_b32_e32 v161, 0xffff0000, v163
	v_pk_mul_f32 v[92:93], v[92:93], v[86:87]
	v_lshlrev_b32_e32 v86, 16, v88
	v_and_b32_e32 v87, 0xffff0000, v88
	v_pk_mul_f32 v[164:165], v[122:123], v[164:165]
	v_pk_mul_f32 v[170:171], v[128:129], v[160:161]
	v_pk_mul_f32 v[94:95], v[94:95], v[86:87]
	v_lshlrev_b32_e32 v86, 16, v89
	v_and_b32_e32 v87, 0xffff0000, v89
	v_cvt_pk_bf16_f32 v160, v164, v165
	v_cvt_pk_bf16_f32 v161, v166, v167
	v_cvt_pk_bf16_f32 v162, v168, v169
	v_cvt_pk_bf16_f32 v163, v170, v171
	v_pk_mul_f32 v[96:97], v[96:97], v[86:87]
	v_cvt_pk_bf16_f32 v86, v90, v91
	v_mfma_f32_32x32x16_bf16 v[66:81], v[98:101], v[160:163], v[66:81]
	ds_read_b128 v[160:163], v154 offset:8736
	v_cvt_pk_bf16_f32 v87, v92, v93
	v_cvt_pk_bf16_f32 v88, v94, v95
	v_cvt_pk_bf16_f32 v89, v96, v97
	s_waitcnt lgkmcnt(0)
	v_lshlrev_b32_e32 v164, 16, v160
	v_and_b32_e32 v165, 0xffff0000, v160
	v_mfma_f32_32x32x16_bf16 v[82:97], v[82:85], v[86:89], 0
	v_lshlrev_b32_e32 v160, 16, v161
	v_and_b32_e32 v161, 0xffff0000, v161
	v_mul_f32_e64 v124, v124, v160
	v_mul_f32_e64 v125, v125, v161
	v_lshlrev_b32_e32 v160, 16, v162
	v_and_b32_e32 v161, 0xffff0000, v162
	v_pk_mul_f32 v[126:127], v[126:127], v[160:161]
	v_lshlrev_b32_e32 v160, 16, v163
	v_and_b32_e32 v161, 0xffff0000, v163
	v_pk_mul_f32 v[122:123], v[122:123], v[164:165]
	v_pk_mul_f32 v[128:129], v[128:129], v[160:161]
	v_cvt_pk_bf16_f32 v122, v122, v123
	v_cvt_pk_bf16_f32 v123, v124, v125
	v_cvt_pk_bf16_f32 v124, v126, v127
	v_cvt_pk_bf16_f32 v125, v128, v129
	s_nop 1
	v_mfma_f32_32x32x16_bf16 v[82:97], v[98:101], v[122:125], v[82:97]
	ds_read_b128 v[98:101], v130 offset:128
	s_waitcnt lgkmcnt(0)
	v_sub_f32_e32 v98, v158, v98
	v_mul_f32_e32 v98, 0x3fb8aa3b, v98
	v_exp_f32_e32 v126, v98
	v_sub_f32_e32 v98, v158, v99
	v_mul_f32_e32 v98, 0x3fb8aa3b, v98
	v_exp_f32_e32 v127, v98
	v_sub_f32_e32 v98, v158, v100
	v_mul_f32_e32 v98, 0x3fb8aa3b, v98
	v_exp_f32_e32 v128, v98
	v_sub_f32_e32 v98, v158, v101
	v_mul_f32_e32 v98, 0x3fb8aa3b, v98
	v_exp_f32_e32 v129, v98
	ds_read_b128 v[98:101], v130 offset:144
	s_waitcnt lgkmcnt(0)
	v_sub_f32_e32 v98, v158, v98
	v_mul_f32_e32 v98, 0x3fb8aa3b, v98
	v_exp_f32_e32 v160, v98
	v_sub_f32_e32 v98, v158, v99
	v_mul_f32_e32 v98, 0x3fb8aa3b, v98
	v_exp_f32_e32 v161, v98
	v_sub_f32_e32 v98, v158, v100
	v_mul_f32_e32 v98, 0x3fb8aa3b, v98
	v_exp_f32_e32 v162, v98
	v_sub_f32_e32 v98, v158, v101
	v_mul_f32_e32 v98, 0x3fb8aa3b, v98
	v_exp_f32_e32 v163, v98
	ds_read_b128 v[98:101], v142 offset:34880
	ds_read_b128 v[122:125], v154 offset:64
	s_waitcnt lgkmcnt(0)
; DI float bflo(unsigned u) { return __uint_as_float(u << 16); }
; DI float bfhi(unsigned u) { return __uint_as_float(u & 0xffff0000u); }
; DI f32x16 mfma32(bf16x8 a, bf16x8 b, f32x16 c) { return __builtin_amdgcn_mfma_f32_32x32x16_bf16(a, b, c, 0, 0, 0); }
; DI void ssd_a_item(PP p, int layer, int item, unsigned char* lds) {
;     ...
;             for (int kk = 0; kk < 8; ++kk) {
;                 float wl[8];
; #pragma unroll
;                 for (int e = 0; e < 8; ++e) wl[e] = __expf(acs_last - Acs[kk * 16 + 8 * hh + e]);
;                 const bf16x8 a = ld16(Bt + (w * 32 + l31) * SSTR + kk * 16 + 8 * hh);
; #pragma unroll
;                 for (int pb = 0; pb < 2; ++pb) {
;                     const u32x4 xr = *(const u32x4*)(Xt + (pb * 32 + l31) * SSTR + kk * 16 + 8 * hh);
;                     const bf16x8 xb = pack8(bflo(xr[0]) * wl[0], bfhi(xr[0]) * wl[1], bflo(xr[1]) * wl[2], bfhi(xr[1]) * wl[3],
;                                             bflo(xr[2]) * wl[4], bfhi(xr[2]) * wl[5], bflo(xr[3]) * wl[6], bfhi(xr[3]) * wl[7]);
;                     la[pb] = mfma32(a, xb, la[pb]);
;                 }
	v_lshlrev_b32_e32 v164, 16, v122
	v_and_b32_e32 v165, 0xffff0000, v122
	v_lshlrev_b32_e32 v122, 16, v123
	v_and_b32_e32 v123, 0xffff0000, v123
	v_pk_mul_f32 v[166:167], v[128:129], v[122:123]
	v_lshlrev_b32_e32 v122, 16, v124
	v_and_b32_e32 v123, 0xffff0000, v124
	v_pk_mul_f32 v[168:169], v[160:161], v[122:123]
	v_lshlrev_b32_e32 v122, 16, v125
	v_and_b32_e32 v123, 0xffff0000, v125
	v_pk_mul_f32 v[164:165], v[126:127], v[164:165]
	v_pk_mul_f32 v[170:171], v[162:163], v[122:123]
	v_cvt_pk_bf16_f32 v122, v164, v165
	v_cvt_pk_bf16_f32 v123, v166, v167
	v_cvt_pk_bf16_f32 v124, v168, v169
	v_cvt_pk_bf16_f32 v125, v170, v171
	s_nop 1
	v_mfma_f32_32x32x16_bf16 v[66:81], v[98:101], v[122:125], v[66:81]
	ds_read_b128 v[122:125], v154 offset:8768
	s_waitcnt lgkmcnt(0)
	v_lshlrev_b32_e32 v164, 16, v122
	v_and_b32_e32 v165, 0xffff0000, v122
	v_lshlrev_b32_e32 v122, 16, v123
	v_and_b32_e32 v123, 0xffff0000, v123
	v_pk_mul_f32 v[128:129], v[128:129], v[122:123]
	v_lshlrev_b32_e32 v122, 16, v124
	v_and_b32_e32 v123, 0xffff0000, v124
	v_pk_mul_f32 v[160:161], v[160:161], v[122:123]
	v_lshlrev_b32_e32 v122, 16, v125
	v_and_b32_e32 v123, 0xffff0000, v125
	v_pk_mul_f32 v[126:127], v[126:127], v[164:165]
	v_pk_mul_f32 v[162:163], v[162:163], v[122:123]
	v_cvt_pk_bf16_f32 v122, v126, v127
	v_cvt_pk_bf16_f32 v123, v128, v129
	v_cvt_pk_bf16_f32 v124, v160, v161
	v_cvt_pk_bf16_f32 v125, v162, v163
	s_nop 1
	v_mfma_f32_32x32x16_bf16 v[82:97], v[98:101], v[122:125], v[82:97]
	ds_read_b128 v[98:101], v130 offset:192
	s_waitcnt lgkmcnt(0)
	v_sub_f32_e32 v98, v158, v98
	v_mul_f32_e32 v98, 0x3fb8aa3b, v98
	v_exp_f32_e32 v122, v98
	v_sub_f32_e32 v98, v158, v99
	v_mul_f32_e32 v98, 0x3fb8aa3b, v98
	v_exp_f32_e32 v123, v98
	v_sub_f32_e32 v98, v158, v100
	v_mul_f32_e32 v98, 0x3fb8aa3b, v98
	v_exp_f32_e32 v124, v98
	v_sub_f32_e32 v98, v158, v101
	v_mul_f32_e32 v98, 0x3fb8aa3b, v98
	v_exp_f32_e32 v125, v98
	ds_read_b128 v[98:101], v130 offset:208
	s_waitcnt lgkmcnt(0)
	v_sub_f32_e32 v98, v158, v98
	v_mul_f32_e32 v98, 0x3fb8aa3b, v98
	v_exp_f32_e32 v126, v98
	v_sub_f32_e32 v98, v158, v99
	v_mul_f32_e32 v98, 0x3fb8aa3b, v98
	v_exp_f32_e32 v127, v98
	v_sub_f32_e32 v98, v158, v100
	v_mul_f32_e32 v98, 0x3fb8aa3b, v98
	v_exp_f32_e32 v128, v98
	v_sub_f32_e32 v98, v158, v101
	v_mul_f32_e32 v98, 0x3fb8aa3b, v98
	v_exp_f32_e32 v129, v98
	ds_read_b128 v[98:101], v142 offset:34912
	ds_read_b128 v[160:163], v154 offset:96
	s_waitcnt lgkmcnt(0)
	v_lshlrev_b32_e32 v164, 16, v160
	v_and_b32_e32 v165, 0xffff0000, v160
	v_lshlrev_b32_e32 v160, 16, v161
	v_and_b32_e32 v161, 0xffff0000, v161
	v_pk_mul_f32 v[166:167], v[124:125], v[160:161]
	v_lshlrev_b32_e32 v160, 16, v162
	v_and_b32_e32 v161, 0xffff0000, v162
	v_pk_mul_f32 v[168:169], v[126:127], v[160:161]
	v_lshlrev_b32_e32 v160, 16, v163
	v_and_b32_e32 v161, 0xffff0000, v163
	v_pk_mul_f32 v[164:165], v[122:123], v[164:165]
	v_pk_mul_f32 v[170:171], v[128:129], v[160:161]
	v_cvt_pk_bf16_f32 v160, v164, v165
	v_cvt_pk_bf16_f32 v161, v166, v167
	v_cvt_pk_bf16_f32 v162, v168, v169
	v_cvt_pk_bf16_f32 v163, v170, v171
	s_nop 1
	v_mfma_f32_32x32x16_bf16 v[66:81], v[98:101], v[160:163], v[66:81]
	ds_read_b128 v[160:163], v154 offset:8800
	s_waitcnt lgkmcnt(0)
	v_lshlrev_b32_e32 v164, 16, v160
	v_and_b32_e32 v165, 0xffff0000, v160
	v_lshlrev_b32_e32 v160, 16, v161
	v_and_b32_e32 v161, 0xffff0000, v161
	v_pk_mul_f32 v[124:125], v[124:125], v[160:161]
	v_lshlrev_b32_e32 v160, 16, v162
	v_and_b32_e32 v161, 0xffff0000, v162
	v_pk_mul_f32 v[126:127], v[126:127], v[160:161]
	v_lshlrev_b32_e32 v160, 16, v163
	v_and_b32_e32 v161, 0xffff0000, v163
	v_pk_mul_f32 v[122:123], v[122:123], v[164:165]
	v_pk_mul_f32 v[128:129], v[128:129], v[160:161]
	v_cvt_pk_bf16_f32 v122, v122, v123
	v_cvt_pk_bf16_f32 v123, v124, v125
	v_cvt_pk_bf16_f32 v124, v126, v127
	v_cvt_pk_bf16_f32 v125, v128, v129
	s_nop 1
	v_mfma_f32_32x32x16_bf16 v[82:97], v[98:101], v[122:125], v[82:97]
	ds_read_b128 v[98:101], v130 offset:256
	s_waitcnt lgkmcnt(0)
	v_sub_f32_e32 v98, v158, v98
	v_mul_f32_e32 v98, 0x3fb8aa3b, v98
	v_exp_f32_e32 v126, v98
	v_sub_f32_e32 v98, v158, v99
	v_mul_f32_e32 v98, 0x3fb8aa3b, v98
	v_exp_f32_e32 v127, v98
	v_sub_f32_e32 v98, v158, v100
	v_mul_f32_e32 v98, 0x3fb8aa3b, v98
	v_exp_f32_e32 v128, v98
	v_sub_f32_e32 v98, v158, v101
	v_mul_f32_e32 v98, 0x3fb8aa3b, v98
	v_exp_f32_e32 v129, v98
	ds_read_b128 v[98:101], v130 offset:272
	s_waitcnt lgkmcnt(0)
	v_sub_f32_e32 v98, v158, v98
	v_mul_f32_e32 v98, 0x3fb8aa3b, v98
	v_exp_f32_e32 v160, v98
	v_sub_f32_e32 v98, v158, v99
	v_mul_f32_e32 v98, 0x3fb8aa3b, v98
	v_exp_f32_e32 v161, v98
	v_sub_f32_e32 v98, v158, v100
	v_mul_f32_e32 v98, 0x3fb8aa3b, v98
	v_exp_f32_e32 v162, v98
	v_sub_f32_e32 v98, v158, v101
	v_mul_f32_e32 v98, 0x3fb8aa3b, v98
	v_exp_f32_e32 v163, v98
	ds_read_b128 v[98:101], v142 offset:34944
	ds_read_b128 v[122:125], v154 offset:128
	s_waitcnt lgkmcnt(0)
	v_lshlrev_b32_e32 v164, 16, v122
	v_and_b32_e32 v165, 0xffff0000, v122
	v_lshlrev_b32_e32 v122, 16, v123
	v_and_b32_e32 v123, 0xffff0000, v123
	v_pk_mul_f32 v[166:167], v[128:129], v[122:123]
	v_lshlrev_b32_e32 v122, 16, v124
	v_and_b32_e32 v123, 0xffff0000, v124
	v_pk_mul_f32 v[168:169], v[160:161], v[122:123]
	v_lshlrev_b32_e32 v122, 16, v125
	v_and_b32_e32 v123, 0xffff0000, v125
	v_pk_mul_f32 v[164:165], v[126:127], v[164:165]
	v_pk_mul_f32 v[170:171], v[162:163], v[122:123]
	v_cvt_pk_bf16_f32 v122, v164, v165
	v_cvt_pk_bf16_f32 v123, v166, v167
	v_cvt_pk_bf16_f32 v124, v168, v169
	v_cvt_pk_bf16_f32 v125, v170, v171
	s_nop 1
	v_mfma_f32_32x32x16_bf16 v[66:81], v[98:101], v[122:125], v[66:81]
	ds_read_b128 v[122:125], v154 offset:8832
	s_waitcnt lgkmcnt(0)
; DI float bflo(unsigned u) { return __uint_as_float(u << 16); }
; DI float bfhi(unsigned u) { return __uint_as_float(u & 0xffff0000u); }
; DI f32x16 mfma32(bf16x8 a, bf16x8 b, f32x16 c) { return __builtin_amdgcn_mfma_f32_32x32x16_bf16(a, b, c, 0, 0, 0); }
; DI void ssd_a_item(PP p, int layer, int item, unsigned char* lds) {
;     ...
;             for (int kk = 0; kk < 8; ++kk) {
;                 float wl[8];
; #pragma unroll
;                 for (int e = 0; e < 8; ++e) wl[e] = __expf(acs_last - Acs[kk * 16 + 8 * hh + e]);
;                 const bf16x8 a = ld16(Bt + (w * 32 + l31) * SSTR + kk * 16 + 8 * hh);
; #pragma unroll
;                 for (int pb = 0; pb < 2; ++pb) {
;                     const u32x4 xr = *(const u32x4*)(Xt + (pb * 32 + l31) * SSTR + kk * 16 + 8 * hh);
;                     const bf16x8 xb = pack8(bflo(xr[0]) * wl[0], bfhi(xr[0]) * wl[1], bflo(xr[1]) * wl[2], bfhi(xr[1]) * wl[3],
;                                             bflo(xr[2]) * wl[4], bfhi(xr[2]) * wl[5], bflo(xr[3]) * wl[6], bfhi(xr[3]) * wl[7]);
;                     la[pb] = mfma32(a, xb, la[pb]);
;                 }
	v_lshlrev_b32_e32 v164, 16, v122
	v_and_b32_e32 v165, 0xffff0000, v122
	v_lshlrev_b32_e32 v122, 16, v123
	v_and_b32_e32 v123, 0xffff0000, v123
	v_pk_mul_f32 v[128:129], v[128:129], v[122:123]
	v_lshlrev_b32_e32 v122, 16, v124
	v_and_b32_e32 v123, 0xffff0000, v124
	v_pk_mul_f32 v[160:161], v[160:161], v[122:123]
	v_lshlrev_b32_e32 v122, 16, v125
	v_and_b32_e32 v123, 0xffff0000, v125
	v_pk_mul_f32 v[126:127], v[126:127], v[164:165]
	v_pk_mul_f32 v[162:163], v[162:163], v[122:123]
	v_cvt_pk_bf16_f32 v122, v126, v127
	v_cvt_pk_bf16_f32 v123, v128, v129
	v_cvt_pk_bf16_f32 v124, v160, v161
	v_cvt_pk_bf16_f32 v125, v162, v163
	s_nop 1
	v_mfma_f32_32x32x16_bf16 v[82:97], v[98:101], v[122:125], v[82:97]
	ds_read_b128 v[98:101], v130 offset:320
	s_waitcnt lgkmcnt(0)
	v_sub_f32_e32 v98, v158, v98
	v_mul_f32_e32 v98, 0x3fb8aa3b, v98
	v_exp_f32_e32 v122, v98
	v_sub_f32_e32 v98, v158, v99
	v_mul_f32_e32 v98, 0x3fb8aa3b, v98
	v_exp_f32_e32 v123, v98
	v_sub_f32_e32 v98, v158, v100
	v_mul_f32_e32 v98, 0x3fb8aa3b, v98
	v_exp_f32_e32 v124, v98
	v_sub_f32_e32 v98, v158, v101
	v_mul_f32_e32 v98, 0x3fb8aa3b, v98
	v_exp_f32_e32 v125, v98
	ds_read_b128 v[98:101], v130 offset:336
	s_waitcnt lgkmcnt(0)
	v_sub_f32_e32 v98, v158, v98
	v_mul_f32_e32 v98, 0x3fb8aa3b, v98
	v_exp_f32_e32 v126, v98
	v_sub_f32_e32 v98, v158, v99
	v_mul_f32_e32 v98, 0x3fb8aa3b, v98
	v_exp_f32_e32 v127, v98
	v_sub_f32_e32 v98, v158, v100
	v_mul_f32_e32 v98, 0x3fb8aa3b, v98
	v_exp_f32_e32 v128, v98
	v_sub_f32_e32 v98, v158, v101
	v_mul_f32_e32 v98, 0x3fb8aa3b, v98
	v_exp_f32_e32 v129, v98
	ds_read_b128 v[98:101], v142 offset:34976
	ds_read_b128 v[160:163], v154 offset:160
	s_waitcnt lgkmcnt(0)
	v_lshlrev_b32_e32 v164, 16, v160
	v_and_b32_e32 v165, 0xffff0000, v160
	v_lshlrev_b32_e32 v160, 16, v161
	v_and_b32_e32 v161, 0xffff0000, v161
	v_pk_mul_f32 v[166:167], v[124:125], v[160:161]
	v_lshlrev_b32_e32 v160, 16, v162
	v_and_b32_e32 v161, 0xffff0000, v162
	v_pk_mul_f32 v[168:169], v[126:127], v[160:161]
	v_lshlrev_b32_e32 v160, 16, v163
	v_and_b32_e32 v161, 0xffff0000, v163
	v_pk_mul_f32 v[164:165], v[122:123], v[164:165]
	v_pk_mul_f32 v[170:171], v[128:129], v[160:161]
	v_cvt_pk_bf16_f32 v160, v164, v165
	v_cvt_pk_bf16_f32 v161, v166, v167
	v_cvt_pk_bf16_f32 v162, v168, v169
	v_cvt_pk_bf16_f32 v163, v170, v171
	s_nop 1
	v_mfma_f32_32x32x16_bf16 v[66:81], v[98:101], v[160:163], v[66:81]
	ds_read_b128 v[160:163], v154 offset:8864
	s_waitcnt lgkmcnt(0)
	v_lshlrev_b32_e32 v164, 16, v160
	v_and_b32_e32 v165, 0xffff0000, v160
	v_lshlrev_b32_e32 v160, 16, v161
	v_and_b32_e32 v161, 0xffff0000, v161
	v_pk_mul_f32 v[124:125], v[124:125], v[160:161]
	v_lshlrev_b32_e32 v160, 16, v162
	v_and_b32_e32 v161, 0xffff0000, v162
	v_pk_mul_f32 v[126:127], v[126:127], v[160:161]
	v_lshlrev_b32_e32 v160, 16, v163
	v_and_b32_e32 v161, 0xffff0000, v163
	v_pk_mul_f32 v[122:123], v[122:123], v[164:165]
	v_pk_mul_f32 v[128:129], v[128:129], v[160:161]
	v_cvt_pk_bf16_f32 v122, v122, v123
	v_cvt_pk_bf16_f32 v123, v124, v125
	v_cvt_pk_bf16_f32 v124, v126, v127
	v_cvt_pk_bf16_f32 v125, v128, v129
	s_nop 1
	v_mfma_f32_32x32x16_bf16 v[82:97], v[98:101], v[122:125], v[82:97]
	ds_read_b128 v[98:101], v130 offset:384
	s_waitcnt lgkmcnt(0)
	v_sub_f32_e32 v98, v158, v98
	v_mul_f32_e32 v98, 0x3fb8aa3b, v98
	v_exp_f32_e32 v126, v98
	v_sub_f32_e32 v98, v158, v99
	v_mul_f32_e32 v98, 0x3fb8aa3b, v98
	v_exp_f32_e32 v127, v98
	v_sub_f32_e32 v98, v158, v100
	v_mul_f32_e32 v98, 0x3fb8aa3b, v98
	v_exp_f32_e32 v128, v98
	v_sub_f32_e32 v98, v158, v101
	v_mul_f32_e32 v98, 0x3fb8aa3b, v98
	v_exp_f32_e32 v129, v98
	ds_read_b128 v[98:101], v130 offset:400
	s_waitcnt lgkmcnt(0)
	v_sub_f32_e32 v98, v158, v98
	v_mul_f32_e32 v98, 0x3fb8aa3b, v98
	v_exp_f32_e32 v160, v98
	v_sub_f32_e32 v98, v158, v99
	v_mul_f32_e32 v98, 0x3fb8aa3b, v98
	v_exp_f32_e32 v161, v98
	v_sub_f32_e32 v98, v158, v100
	v_mul_f32_e32 v98, 0x3fb8aa3b, v98
	v_exp_f32_e32 v162, v98
	v_sub_f32_e32 v98, v158, v101
	v_mul_f32_e32 v98, 0x3fb8aa3b, v98
	v_exp_f32_e32 v163, v98
	ds_read_b128 v[98:101], v142 offset:35008
	ds_read_b128 v[122:125], v154 offset:192
	s_waitcnt lgkmcnt(0)
	v_lshlrev_b32_e32 v164, 16, v122
	v_and_b32_e32 v165, 0xffff0000, v122
	v_lshlrev_b32_e32 v122, 16, v123
	v_and_b32_e32 v123, 0xffff0000, v123
	v_pk_mul_f32 v[166:167], v[128:129], v[122:123]
	v_lshlrev_b32_e32 v122, 16, v124
	v_and_b32_e32 v123, 0xffff0000, v124
	v_pk_mul_f32 v[168:169], v[160:161], v[122:123]
	v_lshlrev_b32_e32 v122, 16, v125
	v_and_b32_e32 v123, 0xffff0000, v125
	v_pk_mul_f32 v[164:165], v[126:127], v[164:165]
	v_pk_mul_f32 v[170:171], v[162:163], v[122:123]
	v_cvt_pk_bf16_f32 v122, v164, v165
	v_cvt_pk_bf16_f32 v123, v166, v167
	v_cvt_pk_bf16_f32 v124, v168, v169
	v_cvt_pk_bf16_f32 v125, v170, v171
	s_nop 1
	v_mfma_f32_32x32x16_bf16 v[66:81], v[98:101], v[122:125], v[66:81]
	ds_read_b128 v[122:125], v154 offset:8896
	s_waitcnt lgkmcnt(0)
; DI float bflo(unsigned u) { return __uint_as_float(u << 16); }
; DI float bfhi(unsigned u) { return __uint_as_float(u & 0xffff0000u); }
; DI f32x16 mfma32(bf16x8 a, bf16x8 b, f32x16 c) { return __builtin_amdgcn_mfma_f32_32x32x16_bf16(a, b, c, 0, 0, 0); }
; DI void ssd_a_item(PP p, int layer, int item, unsigned char* lds) {
;     ...
;     for (int j = hhalf * 4; j < hhalf * 4 + 4; ++j) {
;         const int head = g * 8 + j;
;     ...
; #pragma unroll
;                 for (int e = 0; e < 8; ++e) wl[e] = __expf(acs_last - Acs[kk * 16 + 8 * hh + e]);
;                 const bf16x8 a = ld16(Bt + (w * 32 + l31) * SSTR + kk * 16 + 8 * hh);
; #pragma unroll
;                 for (int pb = 0; pb < 2; ++pb) {
;                     const u32x4 xr = *(const u32x4*)(Xt + (pb * 32 + l31) * SSTR + kk * 16 + 8 * hh);
;                     const bf16x8 xb = pack8(bflo(xr[0]) * wl[0], bfhi(xr[0]) * wl[1], bflo(xr[1]) * wl[2], bfhi(xr[1]) * wl[3],
;                                             bflo(xr[2]) * wl[4], bfhi(xr[2]) * wl[5], bflo(xr[3]) * wl[6], bfhi(xr[3]) * wl[7]);
;                     la[pb] = mfma32(a, xb, la[pb]);
;                 }
;             }
; #pragma unroll
;             for (int pb = 0; pb < 2; ++pb) {
;                 bf16_t* dst = p->hb + ((((size_t)(bc * 16 + head) * 2 + pb) * 4 + w) * 64 + lane) * 16;
;                 *(bf16x8*)dst = pack_step(la[pb], 0);
;                 *(bf16x8*)(dst + 8) = pack_step(la[pb], 1);
;             }
;         }
;         __syncthreads();
	v_lshlrev_b32_e32 v164, 16, v122
	v_and_b32_e32 v165, 0xffff0000, v122
	v_lshlrev_b32_e32 v122, 16, v123
	v_and_b32_e32 v123, 0xffff0000, v123
	v_pk_mul_f32 v[128:129], v[128:129], v[122:123]
	v_lshlrev_b32_e32 v122, 16, v124
	v_and_b32_e32 v123, 0xffff0000, v124
	v_pk_mul_f32 v[160:161], v[160:161], v[122:123]
	v_lshlrev_b32_e32 v122, 16, v125
	v_and_b32_e32 v123, 0xffff0000, v125
	v_pk_mul_f32 v[126:127], v[126:127], v[164:165]
	v_pk_mul_f32 v[162:163], v[162:163], v[122:123]
	v_cvt_pk_bf16_f32 v122, v126, v127
	v_cvt_pk_bf16_f32 v123, v128, v129
	v_cvt_pk_bf16_f32 v124, v160, v161
	v_cvt_pk_bf16_f32 v125, v162, v163
	s_nop 1
	v_mfma_f32_32x32x16_bf16 v[82:97], v[98:101], v[122:125], v[82:97]
	ds_read_b128 v[98:101], v130 offset:448
	s_waitcnt lgkmcnt(0)
	v_sub_f32_e32 v98, v158, v98
	v_mul_f32_e32 v98, 0x3fb8aa3b, v98
	v_exp_f32_e32 v122, v98
	v_sub_f32_e32 v98, v158, v99
	v_mul_f32_e32 v98, 0x3fb8aa3b, v98
	v_exp_f32_e32 v123, v98
	v_sub_f32_e32 v98, v158, v100
	v_mul_f32_e32 v98, 0x3fb8aa3b, v98
	v_exp_f32_e32 v124, v98
	v_sub_f32_e32 v98, v158, v101
	v_mul_f32_e32 v98, 0x3fb8aa3b, v98
	v_exp_f32_e32 v125, v98
	ds_read_b128 v[98:101], v130 offset:464
	s_waitcnt lgkmcnt(0)
	v_sub_f32_e32 v98, v158, v98
	v_mul_f32_e32 v98, 0x3fb8aa3b, v98
	v_exp_f32_e32 v126, v98
	v_sub_f32_e32 v98, v158, v99
	v_mul_f32_e32 v98, 0x3fb8aa3b, v98
	v_exp_f32_e32 v127, v98
	v_sub_f32_e32 v98, v158, v100
	v_mul_f32_e32 v98, 0x3fb8aa3b, v98
	v_exp_f32_e32 v128, v98
	v_sub_f32_e32 v98, v158, v101
	v_mul_f32_e32 v98, 0x3fb8aa3b, v98
	v_exp_f32_e32 v129, v98
	ds_read_b128 v[98:101], v142 offset:35040
	ds_read_b128 v[158:161], v154 offset:224
	s_waitcnt lgkmcnt(0)
	v_lshlrev_b32_e32 v130, 16, v158
	v_and_b32_e32 v131, 0xffff0000, v158
	v_lshlrev_b32_e32 v158, 16, v159
	v_and_b32_e32 v159, 0xffff0000, v159
	v_pk_mul_f32 v[162:163], v[124:125], v[158:159]
	v_lshlrev_b32_e32 v158, 16, v160
	v_and_b32_e32 v159, 0xffff0000, v160
	v_pk_mul_f32 v[164:165], v[126:127], v[158:159]
	v_lshlrev_b32_e32 v158, 16, v161
	v_and_b32_e32 v159, 0xffff0000, v161
	v_pk_mul_f32 v[130:131], v[122:123], v[130:131]
	v_pk_mul_f32 v[166:167], v[128:129], v[158:159]
	v_cvt_pk_bf16_f32 v158, v130, v131
	v_cvt_pk_bf16_f32 v159, v162, v163
	v_cvt_pk_bf16_f32 v160, v164, v165
	v_cvt_pk_bf16_f32 v161, v166, v167
	s_nop 1
	v_mfma_f32_32x32x16_bf16 v[66:81], v[98:101], v[158:161], v[66:81]
	ds_read_b128 v[158:161], v154 offset:8928
	s_waitcnt lgkmcnt(0)
	v_lshlrev_b32_e32 v130, 16, v158
	v_and_b32_e32 v131, 0xffff0000, v158
	v_mul_f32_e64 v122, v122, v130
	v_mul_f32_e64 v123, v123, v131
	v_lshlrev_b32_e32 v130, 16, v159
	v_and_b32_e32 v131, 0xffff0000, v159
	v_pk_mul_f32 v[124:125], v[124:125], v[130:131]
	v_lshlrev_b32_e32 v130, 16, v160
	v_and_b32_e32 v131, 0xffff0000, v160
	v_pk_mul_f32 v[126:127], v[126:127], v[130:131]
	v_lshlrev_b32_e32 v130, 16, v161
	v_and_b32_e32 v131, 0xffff0000, v161
	v_pk_mul_f32 v[128:129], v[128:129], v[130:131]
	v_cvt_pk_bf16_f32 v122, v122, v123
	v_cvt_pk_bf16_f32 v123, v124, v125
	v_cvt_pk_bf16_f32 v124, v126, v127
	v_cvt_pk_bf16_f32 v125, v128, v129
	v_cvt_pk_bf16_f32 v66, v66, v67
	v_cvt_pk_bf16_f32 v67, v68, v69
	v_mfma_f32_32x32x16_bf16 v[82:97], v[98:101], v[122:125], v[82:97]
	v_add_u32_e32 v98, v157, v144
	v_ashrrev_i32_e32 v99, 31, v98
	v_lshlrev_b64 v[98:99], 14, v[98:99]
	v_lshl_add_u64 v[98:99], v[112:113], 0, v[98:99]
	v_cvt_pk_bf16_f32 v68, v70, v71
	v_cvt_pk_bf16_f32 v69, v72, v73
	global_store_dwordx4 v[98:99], v[66:69], off
	v_add_co_u32_e32 v70, vcc, s16, v98
	s_nop 0
	v_cvt_pk_bf16_f32 v66, v74, v75
	v_cvt_pk_bf16_f32 v67, v76, v77
	v_cvt_pk_bf16_f32 v68, v78, v79
	v_cvt_pk_bf16_f32 v69, v80, v81
	global_store_dwordx4 v[98:99], v[66:69], off offset:16
	v_addc_co_u32_e32 v71, vcc, 0, v99, vcc
	s_nop 0
	v_cvt_pk_bf16_f32 v66, v82, v83
	v_cvt_pk_bf16_f32 v67, v84, v85
	v_cvt_pk_bf16_f32 v68, v86, v87
	v_cvt_pk_bf16_f32 v69, v88, v89
	global_store_dwordx4 v[70:71], v[66:69], off
	s_mov_b64 s[16:17], 0x80
	v_cmp_eq_u32_e32 vcc, v156, v220
	v_cvt_pk_bf16_f32 v66, v90, v91
	v_cvt_pk_bf16_f32 v67, v92, v93
	v_cvt_pk_bf16_f32 v68, v94, v95
	v_cvt_pk_bf16_f32 v69, v96, v97
	global_store_dwordx4 v[70:71], v[66:69], off offset:16
	v_lshl_add_u64 v[120:121], v[120:121], 0, s[16:17]
	s_or_b64 s[58:59], vcc, s[58:59]
	v_add_u32_e32 v66, 1, v156
	v_mov_b32_e32 v156, v66
	s_barrier
	s_andn2_b64 exec, exec, s[58:59]
	s_cbranch_execz .LBB0_504
